# v24 + prep xg_rows hand-rewritten: gain vector loaded once, 4 rows of x in flight with counted vmcnt, the 8 row sums shuffle-reduced together
# speedup vs baseline: 1.0040x; 1.0040x over previous
; DI int TIDX() { int t = (int)threadIdx.x; asm volatile("" : "+v"(t)); return t; }
; DI unsigned pk2(float lo, float hi) { f32x2 v = {lo, hi}; return __builtin_bit_cast(unsigned, __builtin_convertvector(v, bfx2)); }
; DI void xg_rows(const float* x, const float* g, bf16_t* xg, float* ssq, int row0) {
;   const int lane = TIDX() & 63, wid = TIDX() >> 6;
;   for (int rr = 0; rr < 8; ++rr) {
;     const int t = row0 + wid * 8 + rr; const float* xr = x + (size_t)t * D_; float s = 0.f;
; #pragma unroll
;     for (int c = 0; c < 4; ++c) {
;       const int k = c * 256 + lane * 4; const f32x4 v = *(const f32x4*)(xr + k), gv = *(const f32x4*)(g + k);
;       s += v[0] * v[0] + v[1] * v[1] + v[2] * v[2] + v[3] * v[3];
;       *(u32x2*)(xg + (size_t)t * D_ + k) = (u32x2){pk2(v[0] * gv[0], v[1] * gv[1]), pk2(v[2] * gv[2], v[3] * gv[3])};
;     }
; #pragma unroll
;     for (int o = 32; o >= 1; o >>= 1) s += __shfl_xor(s, o);
;     if (lane < 16) ssq[(size_t)t * 16 + lane] = lane == 0 ? s : 0.f;
;   }
; }
.LBB0_14:
	s_waitcnt lgkmcnt(0)
	global_load_dwordx4 v[56:59], v[4:5], off
	global_load_dwordx4 v[60:63], v[4:5], off offset:1024
	global_load_dwordx4 v[64:67], v[4:5], off offset:2048
	global_load_dwordx4 v[68:71], v[4:5], off offset:3072
	v_lshlrev_b32_e32 v160, 12, v18
	v_mov_b32_e32 v161, 0
	v_lshl_add_u64 v[160:161], v[6:7], 0, v[160:161]
	v_lshlrev_b32_e32 v162, 11, v18
	v_mov_b32_e32 v163, 0
	v_lshl_add_u64 v[162:163], v[8:9], 0, v[162:163]
	v_lshlrev_b32_e32 v164, 6, v18
	v_mov_b32_e32 v165, 0
	v_lshl_add_u64 v[164:165], v[2:3], 0, v[164:165]
	s_mov_b32 s100, 0x1000
	s_mov_b32 s101, 0
	s_mov_b32 s98, 0x800
	s_mov_b32 s99, 0
	global_load_dwordx4 v[72:75], v[160:161], off
	global_load_dwordx4 v[76:79], v[160:161], off offset:1024
	global_load_dwordx4 v[80:83], v[160:161], off offset:2048
	global_load_dwordx4 v[84:87], v[160:161], off offset:3072
	v_lshl_add_u64 v[160:161], v[160:161], 0, s[100:101]
	global_load_dwordx4 v[88:91], v[160:161], off
	global_load_dwordx4 v[92:95], v[160:161], off offset:1024
	global_load_dwordx4 v[96:99], v[160:161], off offset:2048
	global_load_dwordx4 v[100:103], v[160:161], off offset:3072
	v_lshl_add_u64 v[160:161], v[160:161], 0, s[100:101]
	global_load_dwordx4 v[104:107], v[160:161], off
	global_load_dwordx4 v[108:111], v[160:161], off offset:1024
	global_load_dwordx4 v[112:115], v[160:161], off offset:2048
	global_load_dwordx4 v[116:119], v[160:161], off offset:3072
	v_lshl_add_u64 v[160:161], v[160:161], 0, s[100:101]
	global_load_dwordx4 v[120:123], v[160:161], off
	global_load_dwordx4 v[124:127], v[160:161], off offset:1024
	global_load_dwordx4 v[128:131], v[160:161], off offset:2048
	global_load_dwordx4 v[132:135], v[160:161], off offset:3072
	v_lshl_add_u64 v[160:161], v[160:161], 0, s[100:101]
	s_waitcnt vmcnt(12)
	v_pk_mul_f32 v[154:155], v[74:75], v[58:59]
	v_pk_mul_f32 v[152:153], v[72:73], v[56:57]
	v_mul_f32_e32 v136, v73, v73
	v_fmac_f32_e32 v136, v72, v72
	v_fmac_f32_e32 v136, v74, v74
	v_fmac_f32_e32 v136, v75, v75
	v_cvt_pk_bf16_f32 v152, v152, v153
	v_cvt_pk_bf16_f32 v153, v154, v155
	global_store_dwordx2 v[162:163], v[152:153], off
	v_pk_mul_f32 v[158:159], v[78:79], v[62:63]
	v_pk_mul_f32 v[156:157], v[76:77], v[60:61]
	v_mul_f32_e32 v144, v77, v77
	v_fmac_f32_e32 v144, v76, v76
	v_fmac_f32_e32 v144, v78, v78
	v_fmac_f32_e32 v144, v79, v79
	v_cvt_pk_bf16_f32 v156, v156, v157
	v_cvt_pk_bf16_f32 v157, v158, v159
	global_store_dwordx2 v[162:163], v[156:157], off offset:512
	v_add_f32_e32 v136, v136, v144
	v_pk_mul_f32 v[154:155], v[82:83], v[66:67]
	v_pk_mul_f32 v[152:153], v[80:81], v[64:65]
	v_mul_f32_e32 v144, v81, v81
	v_fmac_f32_e32 v144, v80, v80
	v_fmac_f32_e32 v144, v82, v82
	v_fmac_f32_e32 v144, v83, v83
	v_cvt_pk_bf16_f32 v152, v152, v153
	v_cvt_pk_bf16_f32 v153, v154, v155
	global_store_dwordx2 v[162:163], v[152:153], off offset:1024
	v_add_f32_e32 v136, v136, v144
	v_pk_mul_f32 v[158:159], v[86:87], v[70:71]
	v_pk_mul_f32 v[156:157], v[84:85], v[68:69]
	v_mul_f32_e32 v144, v85, v85
	v_fmac_f32_e32 v144, v84, v84
	v_fmac_f32_e32 v144, v86, v86
	v_fmac_f32_e32 v144, v87, v87
	v_cvt_pk_bf16_f32 v156, v156, v157
	v_cvt_pk_bf16_f32 v157, v158, v159
	global_store_dwordx2 v[162:163], v[156:157], off offset:1536
	v_add_f32_e32 v136, v136, v144
	v_lshl_add_u64 v[162:163], v[162:163], 0, s[98:99]
	global_load_dwordx4 v[72:75], v[160:161], off
	global_load_dwordx4 v[76:79], v[160:161], off offset:1024
	global_load_dwordx4 v[80:83], v[160:161], off offset:2048
	global_load_dwordx4 v[84:87], v[160:161], off offset:3072
	v_lshl_add_u64 v[160:161], v[160:161], 0, s[100:101]
	s_waitcnt vmcnt(12)
	v_pk_mul_f32 v[168:169], v[90:91], v[58:59]
	v_pk_mul_f32 v[166:167], v[88:89], v[56:57]
	v_mul_f32_e32 v137, v89, v89
	v_fmac_f32_e32 v137, v88, v88
	v_fmac_f32_e32 v137, v90, v90
	v_fmac_f32_e32 v137, v91, v91
	v_cvt_pk_bf16_f32 v166, v166, v167
	v_cvt_pk_bf16_f32 v167, v168, v169
	global_store_dwordx2 v[162:163], v[166:167], off
	v_pk_mul_f32 v[172:173], v[94:95], v[62:63]
	v_pk_mul_f32 v[170:171], v[92:93], v[60:61]
	v_mul_f32_e32 v145, v93, v93
	v_fmac_f32_e32 v145, v92, v92
	v_fmac_f32_e32 v145, v94, v94
	v_fmac_f32_e32 v145, v95, v95
	v_cvt_pk_bf16_f32 v170, v170, v171
	v_cvt_pk_bf16_f32 v171, v172, v173
	global_store_dwordx2 v[162:163], v[170:171], off offset:512
	v_add_f32_e32 v137, v137, v145
	v_pk_mul_f32 v[168:169], v[98:99], v[66:67]
	v_pk_mul_f32 v[166:167], v[96:97], v[64:65]
	v_mul_f32_e32 v145, v97, v97
	v_fmac_f32_e32 v145, v96, v96
	v_fmac_f32_e32 v145, v98, v98
	v_fmac_f32_e32 v145, v99, v99
	v_cvt_pk_bf16_f32 v166, v166, v167
	v_cvt_pk_bf16_f32 v167, v168, v169
	global_store_dwordx2 v[162:163], v[166:167], off offset:1024
	v_add_f32_e32 v137, v137, v145
	v_pk_mul_f32 v[172:173], v[102:103], v[70:71]
	v_pk_mul_f32 v[170:171], v[100:101], v[68:69]
	v_mul_f32_e32 v145, v101, v101
	v_fmac_f32_e32 v145, v100, v100
	v_fmac_f32_e32 v145, v102, v102
	v_fmac_f32_e32 v145, v103, v103
	v_cvt_pk_bf16_f32 v170, v170, v171
	v_cvt_pk_bf16_f32 v171, v172, v173
	global_store_dwordx2 v[162:163], v[170:171], off offset:1536
	v_add_f32_e32 v137, v137, v145
	v_lshl_add_u64 v[162:163], v[162:163], 0, s[98:99]
	global_load_dwordx4 v[88:91], v[160:161], off
	global_load_dwordx4 v[92:95], v[160:161], off offset:1024
	global_load_dwordx4 v[96:99], v[160:161], off offset:2048
	global_load_dwordx4 v[100:103], v[160:161], off offset:3072
	v_lshl_add_u64 v[160:161], v[160:161], 0, s[100:101]
	s_waitcnt vmcnt(12)
; DI int TIDX() { int t = (int)threadIdx.x; asm volatile("" : "+v"(t)); return t; }
; DI unsigned pk2(float lo, float hi) { f32x2 v = {lo, hi}; return __builtin_bit_cast(unsigned, __builtin_convertvector(v, bfx2)); }
; DI void xg_rows(const float* x, const float* g, bf16_t* xg, float* ssq, int row0) {
;   const int lane = TIDX() & 63, wid = TIDX() >> 6;
;   for (int rr = 0; rr < 8; ++rr) {
;     const int t = row0 + wid * 8 + rr; const float* xr = x + (size_t)t * D_; float s = 0.f;
; #pragma unroll
;     for (int c = 0; c < 4; ++c) {
;       const int k = c * 256 + lane * 4; const f32x4 v = *(const f32x4*)(xr + k), gv = *(const f32x4*)(g + k);
;       s += v[0] * v[0] + v[1] * v[1] + v[2] * v[2] + v[3] * v[3];
;       *(u32x2*)(xg + (size_t)t * D_ + k) = (u32x2){pk2(v[0] * gv[0], v[1] * gv[1]), pk2(v[2] * gv[2], v[3] * gv[3])};
;     }
; #pragma unroll
;     for (int o = 32; o >= 1; o >>= 1) s += __shfl_xor(s, o);
;     if (lane < 16) ssq[(size_t)t * 16 + lane] = lane == 0 ? s : 0.f;
;   }
; }
	v_pk_mul_f32 v[154:155], v[106:107], v[58:59]
	v_pk_mul_f32 v[152:153], v[104:105], v[56:57]
	v_mul_f32_e32 v138, v105, v105
	v_fmac_f32_e32 v138, v104, v104
	v_fmac_f32_e32 v138, v106, v106
	v_fmac_f32_e32 v138, v107, v107
	v_cvt_pk_bf16_f32 v152, v152, v153
	v_cvt_pk_bf16_f32 v153, v154, v155
	global_store_dwordx2 v[162:163], v[152:153], off
	v_pk_mul_f32 v[158:159], v[110:111], v[62:63]
	v_pk_mul_f32 v[156:157], v[108:109], v[60:61]
	v_mul_f32_e32 v146, v109, v109
	v_fmac_f32_e32 v146, v108, v108
	v_fmac_f32_e32 v146, v110, v110
	v_fmac_f32_e32 v146, v111, v111
	v_cvt_pk_bf16_f32 v156, v156, v157
	v_cvt_pk_bf16_f32 v157, v158, v159
	global_store_dwordx2 v[162:163], v[156:157], off offset:512
	v_add_f32_e32 v138, v138, v146
	v_pk_mul_f32 v[154:155], v[114:115], v[66:67]
	v_pk_mul_f32 v[152:153], v[112:113], v[64:65]
	v_mul_f32_e32 v146, v113, v113
	v_fmac_f32_e32 v146, v112, v112
	v_fmac_f32_e32 v146, v114, v114
	v_fmac_f32_e32 v146, v115, v115
	v_cvt_pk_bf16_f32 v152, v152, v153
	v_cvt_pk_bf16_f32 v153, v154, v155
	global_store_dwordx2 v[162:163], v[152:153], off offset:1024
	v_add_f32_e32 v138, v138, v146
	v_pk_mul_f32 v[158:159], v[118:119], v[70:71]
	v_pk_mul_f32 v[156:157], v[116:117], v[68:69]
	v_mul_f32_e32 v146, v117, v117
	v_fmac_f32_e32 v146, v116, v116
	v_fmac_f32_e32 v146, v118, v118
	v_fmac_f32_e32 v146, v119, v119
	v_cvt_pk_bf16_f32 v156, v156, v157
	v_cvt_pk_bf16_f32 v157, v158, v159
	global_store_dwordx2 v[162:163], v[156:157], off offset:1536
	v_add_f32_e32 v138, v138, v146
	v_lshl_add_u64 v[162:163], v[162:163], 0, s[98:99]
	global_load_dwordx4 v[104:107], v[160:161], off
	global_load_dwordx4 v[108:111], v[160:161], off offset:1024
	global_load_dwordx4 v[112:115], v[160:161], off offset:2048
	global_load_dwordx4 v[116:119], v[160:161], off offset:3072
	v_lshl_add_u64 v[160:161], v[160:161], 0, s[100:101]
	s_waitcnt vmcnt(12)
	v_pk_mul_f32 v[168:169], v[122:123], v[58:59]
	v_pk_mul_f32 v[166:167], v[120:121], v[56:57]
	v_mul_f32_e32 v139, v121, v121
	v_fmac_f32_e32 v139, v120, v120
	v_fmac_f32_e32 v139, v122, v122
	v_fmac_f32_e32 v139, v123, v123
	v_cvt_pk_bf16_f32 v166, v166, v167
	v_cvt_pk_bf16_f32 v167, v168, v169
	global_store_dwordx2 v[162:163], v[166:167], off
	v_pk_mul_f32 v[172:173], v[126:127], v[62:63]
	v_pk_mul_f32 v[170:171], v[124:125], v[60:61]
	v_mul_f32_e32 v147, v125, v125
	v_fmac_f32_e32 v147, v124, v124
	v_fmac_f32_e32 v147, v126, v126
	v_fmac_f32_e32 v147, v127, v127
	v_cvt_pk_bf16_f32 v170, v170, v171
	v_cvt_pk_bf16_f32 v171, v172, v173
	global_store_dwordx2 v[162:163], v[170:171], off offset:512
	v_add_f32_e32 v139, v139, v147
	v_pk_mul_f32 v[168:169], v[130:131], v[66:67]
	v_pk_mul_f32 v[166:167], v[128:129], v[64:65]
	v_mul_f32_e32 v147, v129, v129
	v_fmac_f32_e32 v147, v128, v128
	v_fmac_f32_e32 v147, v130, v130
	v_fmac_f32_e32 v147, v131, v131
	v_cvt_pk_bf16_f32 v166, v166, v167
	v_cvt_pk_bf16_f32 v167, v168, v169
	global_store_dwordx2 v[162:163], v[166:167], off offset:1024
	v_add_f32_e32 v139, v139, v147
	v_pk_mul_f32 v[172:173], v[134:135], v[70:71]
	v_pk_mul_f32 v[170:171], v[132:133], v[68:69]
	v_mul_f32_e32 v147, v133, v133
	v_fmac_f32_e32 v147, v132, v132
	v_fmac_f32_e32 v147, v134, v134
	v_fmac_f32_e32 v147, v135, v135
	v_cvt_pk_bf16_f32 v170, v170, v171
	v_cvt_pk_bf16_f32 v171, v172, v173
	global_store_dwordx2 v[162:163], v[170:171], off offset:1536
	v_add_f32_e32 v139, v139, v147
	v_lshl_add_u64 v[162:163], v[162:163], 0, s[98:99]
	global_load_dwordx4 v[120:123], v[160:161], off
	global_load_dwordx4 v[124:127], v[160:161], off offset:1024
	global_load_dwordx4 v[128:131], v[160:161], off offset:2048
	global_load_dwordx4 v[132:135], v[160:161], off offset:3072
	v_lshl_add_u64 v[160:161], v[160:161], 0, s[100:101]
	s_waitcnt vmcnt(12)
	v_pk_mul_f32 v[154:155], v[74:75], v[58:59]
	v_pk_mul_f32 v[152:153], v[72:73], v[56:57]
	v_mul_f32_e32 v140, v73, v73
	v_fmac_f32_e32 v140, v72, v72
	v_fmac_f32_e32 v140, v74, v74
	v_fmac_f32_e32 v140, v75, v75
	v_cvt_pk_bf16_f32 v152, v152, v153
	v_cvt_pk_bf16_f32 v153, v154, v155
	global_store_dwordx2 v[162:163], v[152:153], off
	v_pk_mul_f32 v[158:159], v[78:79], v[62:63]
	v_pk_mul_f32 v[156:157], v[76:77], v[60:61]
	v_mul_f32_e32 v148, v77, v77
	v_fmac_f32_e32 v148, v76, v76
	v_fmac_f32_e32 v148, v78, v78
	v_fmac_f32_e32 v148, v79, v79
	v_cvt_pk_bf16_f32 v156, v156, v157
	v_cvt_pk_bf16_f32 v157, v158, v159
	global_store_dwordx2 v[162:163], v[156:157], off offset:512
	v_add_f32_e32 v140, v140, v148
	v_pk_mul_f32 v[154:155], v[82:83], v[66:67]
	v_pk_mul_f32 v[152:153], v[80:81], v[64:65]
	v_mul_f32_e32 v148, v81, v81
	v_fmac_f32_e32 v148, v80, v80
	v_fmac_f32_e32 v148, v82, v82
	v_fmac_f32_e32 v148, v83, v83
	v_cvt_pk_bf16_f32 v152, v152, v153
	v_cvt_pk_bf16_f32 v153, v154, v155
	global_store_dwordx2 v[162:163], v[152:153], off offset:1024
	v_add_f32_e32 v140, v140, v148
	v_pk_mul_f32 v[158:159], v[86:87], v[70:71]
	v_pk_mul_f32 v[156:157], v[84:85], v[68:69]
	v_mul_f32_e32 v148, v85, v85
	v_fmac_f32_e32 v148, v84, v84
	v_fmac_f32_e32 v148, v86, v86
	v_fmac_f32_e32 v148, v87, v87
	v_cvt_pk_bf16_f32 v156, v156, v157
	v_cvt_pk_bf16_f32 v157, v158, v159
	global_store_dwordx2 v[162:163], v[156:157], off offset:1536
	v_add_f32_e32 v140, v140, v148
	v_lshl_add_u64 v[162:163], v[162:163], 0, s[98:99]
	s_waitcnt vmcnt(8)
; DI int TIDX() { int t = (int)threadIdx.x; asm volatile("" : "+v"(t)); return t; }
; DI unsigned pk2(float lo, float hi) { f32x2 v = {lo, hi}; return __builtin_bit_cast(unsigned, __builtin_convertvector(v, bfx2)); }
; DI void xg_rows(const float* x, const float* g, bf16_t* xg, float* ssq, int row0) {
;   const int lane = TIDX() & 63, wid = TIDX() >> 6;
;   for (int rr = 0; rr < 8; ++rr) {
;     const int t = row0 + wid * 8 + rr; const float* xr = x + (size_t)t * D_; float s = 0.f;
; #pragma unroll
;     for (int c = 0; c < 4; ++c) {
;       const int k = c * 256 + lane * 4; const f32x4 v = *(const f32x4*)(xr + k), gv = *(const f32x4*)(g + k);
;       s += v[0] * v[0] + v[1] * v[1] + v[2] * v[2] + v[3] * v[3];
;       *(u32x2*)(xg + (size_t)t * D_ + k) = (u32x2){pk2(v[0] * gv[0], v[1] * gv[1]), pk2(v[2] * gv[2], v[3] * gv[3])};
;     }
; #pragma unroll
;     for (int o = 32; o >= 1; o >>= 1) s += __shfl_xor(s, o);
;     if (lane < 16) ssq[(size_t)t * 16 + lane] = lane == 0 ? s : 0.f;
;   }
; }
	v_pk_mul_f32 v[168:169], v[90:91], v[58:59]
	v_pk_mul_f32 v[166:167], v[88:89], v[56:57]
	v_mul_f32_e32 v141, v89, v89
	v_fmac_f32_e32 v141, v88, v88
	v_fmac_f32_e32 v141, v90, v90
	v_fmac_f32_e32 v141, v91, v91
	v_cvt_pk_bf16_f32 v166, v166, v167
	v_cvt_pk_bf16_f32 v167, v168, v169
	global_store_dwordx2 v[162:163], v[166:167], off
	v_pk_mul_f32 v[172:173], v[94:95], v[62:63]
	v_pk_mul_f32 v[170:171], v[92:93], v[60:61]
	v_mul_f32_e32 v149, v93, v93
	v_fmac_f32_e32 v149, v92, v92
	v_fmac_f32_e32 v149, v94, v94
	v_fmac_f32_e32 v149, v95, v95
	v_cvt_pk_bf16_f32 v170, v170, v171
	v_cvt_pk_bf16_f32 v171, v172, v173
	global_store_dwordx2 v[162:163], v[170:171], off offset:512
	v_add_f32_e32 v141, v141, v149
	v_pk_mul_f32 v[168:169], v[98:99], v[66:67]
	v_pk_mul_f32 v[166:167], v[96:97], v[64:65]
	v_mul_f32_e32 v149, v97, v97
	v_fmac_f32_e32 v149, v96, v96
	v_fmac_f32_e32 v149, v98, v98
	v_fmac_f32_e32 v149, v99, v99
	v_cvt_pk_bf16_f32 v166, v166, v167
	v_cvt_pk_bf16_f32 v167, v168, v169
	global_store_dwordx2 v[162:163], v[166:167], off offset:1024
	v_add_f32_e32 v141, v141, v149
	v_pk_mul_f32 v[172:173], v[102:103], v[70:71]
	v_pk_mul_f32 v[170:171], v[100:101], v[68:69]
	v_mul_f32_e32 v149, v101, v101
	v_fmac_f32_e32 v149, v100, v100
	v_fmac_f32_e32 v149, v102, v102
	v_fmac_f32_e32 v149, v103, v103
	v_cvt_pk_bf16_f32 v170, v170, v171
	v_cvt_pk_bf16_f32 v171, v172, v173
	global_store_dwordx2 v[162:163], v[170:171], off offset:1536
	v_add_f32_e32 v141, v141, v149
	v_lshl_add_u64 v[162:163], v[162:163], 0, s[98:99]
	s_waitcnt vmcnt(4)
	v_pk_mul_f32 v[154:155], v[106:107], v[58:59]
	v_pk_mul_f32 v[152:153], v[104:105], v[56:57]
	v_mul_f32_e32 v142, v105, v105
	v_fmac_f32_e32 v142, v104, v104
	v_fmac_f32_e32 v142, v106, v106
	v_fmac_f32_e32 v142, v107, v107
	v_cvt_pk_bf16_f32 v152, v152, v153
	v_cvt_pk_bf16_f32 v153, v154, v155
	global_store_dwordx2 v[162:163], v[152:153], off
	v_pk_mul_f32 v[158:159], v[110:111], v[62:63]
	v_pk_mul_f32 v[156:157], v[108:109], v[60:61]
	v_mul_f32_e32 v150, v109, v109
	v_fmac_f32_e32 v150, v108, v108
	v_fmac_f32_e32 v150, v110, v110
	v_fmac_f32_e32 v150, v111, v111
	v_cvt_pk_bf16_f32 v156, v156, v157
	v_cvt_pk_bf16_f32 v157, v158, v159
	global_store_dwordx2 v[162:163], v[156:157], off offset:512
	v_add_f32_e32 v142, v142, v150
	v_pk_mul_f32 v[154:155], v[114:115], v[66:67]
	v_pk_mul_f32 v[152:153], v[112:113], v[64:65]
	v_mul_f32_e32 v150, v113, v113
	v_fmac_f32_e32 v150, v112, v112
	v_fmac_f32_e32 v150, v114, v114
	v_fmac_f32_e32 v150, v115, v115
	v_cvt_pk_bf16_f32 v152, v152, v153
	v_cvt_pk_bf16_f32 v153, v154, v155
	global_store_dwordx2 v[162:163], v[152:153], off offset:1024
	v_add_f32_e32 v142, v142, v150
	v_pk_mul_f32 v[158:159], v[118:119], v[70:71]
	v_pk_mul_f32 v[156:157], v[116:117], v[68:69]
	v_mul_f32_e32 v150, v117, v117
	v_fmac_f32_e32 v150, v116, v116
	v_fmac_f32_e32 v150, v118, v118
	v_fmac_f32_e32 v150, v119, v119
	v_cvt_pk_bf16_f32 v156, v156, v157
	v_cvt_pk_bf16_f32 v157, v158, v159
	global_store_dwordx2 v[162:163], v[156:157], off offset:1536
	v_add_f32_e32 v142, v142, v150
	v_lshl_add_u64 v[162:163], v[162:163], 0, s[98:99]
	s_waitcnt vmcnt(0)
	v_pk_mul_f32 v[168:169], v[122:123], v[58:59]
	v_pk_mul_f32 v[166:167], v[120:121], v[56:57]
	v_mul_f32_e32 v143, v121, v121
	v_fmac_f32_e32 v143, v120, v120
	v_fmac_f32_e32 v143, v122, v122
	v_fmac_f32_e32 v143, v123, v123
	v_cvt_pk_bf16_f32 v166, v166, v167
	v_cvt_pk_bf16_f32 v167, v168, v169
	global_store_dwordx2 v[162:163], v[166:167], off
	v_pk_mul_f32 v[172:173], v[126:127], v[62:63]
	v_pk_mul_f32 v[170:171], v[124:125], v[60:61]
	v_mul_f32_e32 v151, v125, v125
	v_fmac_f32_e32 v151, v124, v124
	v_fmac_f32_e32 v151, v126, v126
	v_fmac_f32_e32 v151, v127, v127
	v_cvt_pk_bf16_f32 v170, v170, v171
	v_cvt_pk_bf16_f32 v171, v172, v173
	global_store_dwordx2 v[162:163], v[170:171], off offset:512
	v_add_f32_e32 v143, v143, v151
	v_pk_mul_f32 v[168:169], v[130:131], v[66:67]
	v_pk_mul_f32 v[166:167], v[128:129], v[64:65]
	v_mul_f32_e32 v151, v129, v129
	v_fmac_f32_e32 v151, v128, v128
	v_fmac_f32_e32 v151, v130, v130
	v_fmac_f32_e32 v151, v131, v131
	v_cvt_pk_bf16_f32 v166, v166, v167
	v_cvt_pk_bf16_f32 v167, v168, v169
	global_store_dwordx2 v[162:163], v[166:167], off offset:1024
	v_add_f32_e32 v143, v143, v151
	v_pk_mul_f32 v[172:173], v[134:135], v[70:71]
	v_pk_mul_f32 v[170:171], v[132:133], v[68:69]
	v_mul_f32_e32 v151, v133, v133
	v_fmac_f32_e32 v151, v132, v132
	v_fmac_f32_e32 v151, v134, v134
	v_fmac_f32_e32 v151, v135, v135
	v_cvt_pk_bf16_f32 v170, v170, v171
	v_cvt_pk_bf16_f32 v171, v172, v173
	global_store_dwordx2 v[162:163], v[170:171], off offset:1536
	v_add_f32_e32 v143, v143, v151
	v_lshl_add_u64 v[162:163], v[162:163], 0, s[98:99]
	ds_bpermute_b32 v144, v12, v136
	ds_bpermute_b32 v145, v12, v137
	ds_bpermute_b32 v146, v12, v138
	ds_bpermute_b32 v147, v12, v139
	ds_bpermute_b32 v148, v12, v140
	ds_bpermute_b32 v149, v12, v141
	ds_bpermute_b32 v150, v12, v142
	ds_bpermute_b32 v151, v12, v143
	s_waitcnt lgkmcnt(0)
; DI int TIDX() { int t = (int)threadIdx.x; asm volatile("" : "+v"(t)); return t; }
; DI unsigned pk2(float lo, float hi) { f32x2 v = {lo, hi}; return __builtin_bit_cast(unsigned, __builtin_convertvector(v, bfx2)); }
; DI void xg_rows(const float* x, const float* g, bf16_t* xg, float* ssq, int row0) {
;   const int lane = TIDX() & 63, wid = TIDX() >> 6;
;   for (int rr = 0; rr < 8; ++rr) {
;     const int t = row0 + wid * 8 + rr; const float* xr = x + (size_t)t * D_; float s = 0.f;
; #pragma unroll
;     for (int c = 0; c < 4; ++c) {
;       const int k = c * 256 + lane * 4; const f32x4 v = *(const f32x4*)(xr + k), gv = *(const f32x4*)(g + k);
;       s += v[0] * v[0] + v[1] * v[1] + v[2] * v[2] + v[3] * v[3];
;       *(u32x2*)(xg + (size_t)t * D_ + k) = (u32x2){pk2(v[0] * gv[0], v[1] * gv[1]), pk2(v[2] * gv[2], v[3] * gv[3])};
;     }
; #pragma unroll
;     for (int o = 32; o >= 1; o >>= 1) s += __shfl_xor(s, o);
;     if (lane < 16) ssq[(size_t)t * 16 + lane] = lane == 0 ? s : 0.f;
;   }
; }
	v_add_f32_e32 v136, v136, v144
	v_add_f32_e32 v137, v137, v145
	v_add_f32_e32 v138, v138, v146
	v_add_f32_e32 v139, v139, v147
	v_add_f32_e32 v140, v140, v148
	v_add_f32_e32 v141, v141, v149
	v_add_f32_e32 v142, v142, v150
	v_add_f32_e32 v143, v143, v151
	ds_bpermute_b32 v144, v13, v136
	ds_bpermute_b32 v145, v13, v137
	ds_bpermute_b32 v146, v13, v138
	ds_bpermute_b32 v147, v13, v139
	ds_bpermute_b32 v148, v13, v140
	ds_bpermute_b32 v149, v13, v141
	ds_bpermute_b32 v150, v13, v142
	ds_bpermute_b32 v151, v13, v143
	s_waitcnt lgkmcnt(0)
	v_add_f32_e32 v136, v136, v144
	v_add_f32_e32 v137, v137, v145
	v_add_f32_e32 v138, v138, v146
	v_add_f32_e32 v139, v139, v147
	v_add_f32_e32 v140, v140, v148
	v_add_f32_e32 v141, v141, v149
	v_add_f32_e32 v142, v142, v150
	v_add_f32_e32 v143, v143, v151
	ds_bpermute_b32 v144, v14, v136
	ds_bpermute_b32 v145, v14, v137
	ds_bpermute_b32 v146, v14, v138
	ds_bpermute_b32 v147, v14, v139
	ds_bpermute_b32 v148, v14, v140
	ds_bpermute_b32 v149, v14, v141
	ds_bpermute_b32 v150, v14, v142
	ds_bpermute_b32 v151, v14, v143
	s_waitcnt lgkmcnt(0)
	v_add_f32_e32 v136, v136, v144
	v_add_f32_e32 v137, v137, v145
	v_add_f32_e32 v138, v138, v146
	v_add_f32_e32 v139, v139, v147
	v_add_f32_e32 v140, v140, v148
	v_add_f32_e32 v141, v141, v149
	v_add_f32_e32 v142, v142, v150
	v_add_f32_e32 v143, v143, v151
	ds_bpermute_b32 v144, v15, v136
	ds_bpermute_b32 v145, v15, v137
	ds_bpermute_b32 v146, v15, v138
	ds_bpermute_b32 v147, v15, v139
	ds_bpermute_b32 v148, v15, v140
	ds_bpermute_b32 v149, v15, v141
	ds_bpermute_b32 v150, v15, v142
	ds_bpermute_b32 v151, v15, v143
	s_waitcnt lgkmcnt(0)
	v_add_f32_e32 v136, v136, v144
	v_add_f32_e32 v137, v137, v145
	v_add_f32_e32 v138, v138, v146
	v_add_f32_e32 v139, v139, v147
	v_add_f32_e32 v140, v140, v148
	v_add_f32_e32 v141, v141, v149
	v_add_f32_e32 v142, v142, v150
	v_add_f32_e32 v143, v143, v151
	ds_bpermute_b32 v144, v16, v136
	ds_bpermute_b32 v145, v16, v137
	ds_bpermute_b32 v146, v16, v138
	ds_bpermute_b32 v147, v16, v139
	ds_bpermute_b32 v148, v16, v140
	ds_bpermute_b32 v149, v16, v141
	ds_bpermute_b32 v150, v16, v142
	ds_bpermute_b32 v151, v16, v143
	s_waitcnt lgkmcnt(0)
	v_add_f32_e32 v136, v136, v144
	v_add_f32_e32 v137, v137, v145
	v_add_f32_e32 v138, v138, v146
	v_add_f32_e32 v139, v139, v147
	v_add_f32_e32 v140, v140, v148
	v_add_f32_e32 v141, v141, v149
	v_add_f32_e32 v142, v142, v150
	v_add_f32_e32 v143, v143, v151
	ds_bpermute_b32 v144, v17, v136
	ds_bpermute_b32 v145, v17, v137
	ds_bpermute_b32 v146, v17, v138
	ds_bpermute_b32 v147, v17, v139
	ds_bpermute_b32 v148, v17, v140
	ds_bpermute_b32 v149, v17, v141
	ds_bpermute_b32 v150, v17, v142
	ds_bpermute_b32 v151, v17, v143
	s_waitcnt lgkmcnt(0)
	v_add_f32_e32 v136, v136, v144
	v_add_f32_e32 v137, v137, v145
	v_add_f32_e32 v138, v138, v146
	v_add_f32_e32 v139, v139, v147
	v_add_f32_e32 v140, v140, v148
	v_add_f32_e32 v141, v141, v149
	v_add_f32_e32 v142, v142, v150
	v_add_f32_e32 v143, v143, v151
	s_and_saveexec_b64 s[2:3], vcc
	v_cndmask_b32_e64 v144, 0, v136, s[0:1]
	v_cndmask_b32_e64 v145, 0, v137, s[0:1]
	v_cndmask_b32_e64 v146, 0, v138, s[0:1]
	v_cndmask_b32_e64 v147, 0, v139, s[0:1]
	v_cndmask_b32_e64 v148, 0, v140, s[0:1]
	v_cndmask_b32_e64 v149, 0, v141, s[0:1]
	v_cndmask_b32_e64 v150, 0, v142, s[0:1]
	v_cndmask_b32_e64 v151, 0, v143, s[0:1]
	global_store_dword v[164:165], v144, off
	global_store_dword v[164:165], v145, off offset:64
	global_store_dword v[164:165], v146, off offset:128
	global_store_dword v[164:165], v147, off offset:192
	global_store_dword v[164:165], v148, off offset:256
	global_store_dword v[164:165], v149, off offset:320
	global_store_dword v[164:165], v150, off offset:384
	global_store_dword v[164:165], v151, off offset:448
	s_or_b64 exec, exec, s[2:3]
	s_mov_b32 s20, 8
